# fourier K order further permuted so the 8 column quads sharing a 128-byte line are produced by workgroups of one XCD (blockIdx%8): their 16-byte partial stores merge in that L2
# speedup vs baseline: 1.0335x; 1.0070x over previous
; __device__ __forceinline__ unsigned pk2(float lo, float hi) { unsigned r; asm volatile("v_cvt_pk_bf16_f32 %0, %1, %2" : "=v"(r) : "v"(lo), "v"(hi)); return r; }
; __device__ void fft_item(const Params& p, int item, bool isctx, LAS unsigned char* lds) {
;     ...
;     const int g = quad >> 4, cc0 = 4 * (quad & 15);
; #pragma unroll 1
;     for (int i1 = tid; i1 < N; i1 += 512) {
;         const int k = (int)(__brev((unsigned)i1) >> (32 - logN));
;         const int k2 = (N - k) & (N - 1);
;         const int i2 = (int)(__brev((unsigned)k2) >> (32 - logN));
;         float re[4], im[4];
; #pragma unroll
;         for (int f = 0; f < 2; ++f) {
;             const f32x2 X = data[f * N + i1], Y = data[f * N + i2];
;             re[2 * f] = (X.x + Y.x) * hs; im[2 * f] = (X.y - Y.y) * hs; re[2 * f + 1] = (X.y + Y.y) * hs; im[2 * f + 1] = (Y.x - X.x) * hs;
;         }
;         bf16_t* dst = AM + (size_t)(rowbase + k) * 1280 + 768 + g * 128 + cc0;
;         u32x2 o; o.x = pk2(re[0], re[1]); o.y = pk2(re[2], re[3]);
;         *(u32x2*)dst = o;
;         o.x = pk2(im[0], im[1]); o.y = pk2(im[2], im[3]);
;         *(u32x2*)(dst + 64) = o;
.LBB0_99:
	s_or_b64 exec, exec, s[18:19]
	s_waitcnt lgkmcnt(0)
	s_barrier
	s_and_saveexec_b64 s[18:19], vcc
	s_mov_b32 s11, 0x8d80000
	s_cbranch_execz .LBB0_102
	s_and_b32 s4, s22, 60
	s_mov_b64 s[20:21], 0
	s_lshr_b32 s4, s2, 6
	s_and_b32 s2, s2, 0x38
	s_or_b32 s2, s2, s4
	s_lshl_b32 s2, s2, 4
	s_mov_b32 s22, 0

; __device__ __forceinline__ unsigned pk2(float lo, float hi) { unsigned r; asm volatile("v_cvt_pk_bf16_f32 %0, %1, %2" : "=v"(r) : "v"(lo), "v"(hi)); return r; }
; __device__ void fft_item(const Params& p, int item, bool isctx, LAS unsigned char* lds) {
;     ...
;     const int g = quad >> 4, cc0 = 4 * (quad & 15);
; #pragma unroll 1
;     for (int i1 = tid; i1 < N; i1 += 512) {
;         const int k = (int)(__brev((unsigned)i1) >> (32 - logN));
;         const int k2 = (N - k) & (N - 1);
;         const int i2 = (int)(__brev((unsigned)k2) >> (32 - logN));
;         float re[4], im[4];
; #pragma unroll
;         for (int f = 0; f < 2; ++f) {
;             const f32x2 X = data[f * N + i1], Y = data[f * N + i2];
;             re[2 * f] = (X.x + Y.x) * hs; im[2 * f] = (X.y - Y.y) * hs; re[2 * f + 1] = (X.y + Y.y) * hs; im[2 * f + 1] = (Y.x - X.x) * hs;
;         }
;         bf16_t* dst = AM + (size_t)(rowbase + k) * 1280 + 768 + g * 128 + cc0;
;         u32x2 o; o.x = pk2(re[0], re[1]); o.y = pk2(re[2], re[3]);
;         *(u32x2*)dst = o;
;         o.x = pk2(im[0], im[1]); o.y = pk2(im[2], im[3]);
;         *(u32x2*)(dst + 64) = o;
.LBB0_172:
	s_or_b64 exec, exec, s[18:19]
	s_waitcnt lgkmcnt(0)
	s_barrier
	s_and_saveexec_b64 s[18:19], vcc
	s_cbranch_execz .LBB0_175
	s_lshl_b32 s4, s6, 2
	s_and_b32 s4, s4, 60
	s_mov_b64 s[20:21], 0
	s_lshr_b32 s4, s2, 6
	s_and_b32 s2, s2, 0x38
	s_or_b32 s2, s2, s4
	s_lshl_b32 s2, s2, 4
	s_mov_b32 s22, 0

; #define GAS __attribute__((address_space(1)))
; __device__ void phase_prep(const Params& p, LAS unsigned char* lds) {
;     ...
;             for (int m0 = 0; m0 < 64; m0 += 16) {
;                 float wv[16];
; #pragma unroll
;                 for (int dd = 0; dd < 16; ++dd) wv[dd] = ((GAS const float*)(unsigned long long)wb)[(size_t)(m0 + dd) * 1024];
;                 asm volatile("" ::: "memory");
; #pragma unroll
;                 for (int dd = 0; dd < 16; ++dd) { const int m = m0 + dd; const float w = wv[dd];
; #pragma unroll
;                     for (int q = 0; q < 8; ++q) a[q] += scr[(m * (8 * co + q)) & 63] * w; }
;             }
.LBB0_693:
	s_lshl_b32 s2, s1, 10
	s_or_b32 s25, s1, 1
	v_lshl_add_u64 v[58:59], s[2:3], 2, v[2:3]
	s_lshl_b32 s2, s25, 10
	s_or_b32 s24, s1, 2
	global_load_dword v80, v[58:59], off
	v_lshl_add_u64 v[58:59], s[2:3], 2, v[2:3]
	s_lshl_b32 s2, s24, 10
	global_load_dword v82, v[58:59], off
	v_lshl_add_u64 v[58:59], s[2:3], 2, v[2:3]
	global_load_dword v86, v[58:59], off
	s_or_b32 s23, s1, 3
	s_lshl_b32 s2, s23, 10
	s_or_b32 s22, s1, 4
	v_lshl_add_u64 v[58:59], s[2:3], 2, v[2:3]
	s_lshl_b32 s2, s22, 10
	s_or_b32 s21, s1, 5
	global_load_dword v88, v[58:59], off
	v_lshl_add_u64 v[58:59], s[2:3], 2, v[2:3]
	s_lshl_b32 s2, s21, 10
	s_or_b32 s20, s1, 6
	global_load_dword v92, v[58:59], off
	v_lshl_add_u64 v[58:59], s[2:3], 2, v[2:3]
	s_lshl_b32 s2, s20, 10
	s_or_b32 s19, s1, 7
	global_load_dword v56, v[58:59], off
	v_lshl_add_u64 v[58:59], s[2:3], 2, v[2:3]
	s_lshl_b32 s2, s19, 10
	s_or_b32 s18, s1, 8
	v_lshl_add_u64 v[60:61], s[2:3], 2, v[2:3]
	s_lshl_b32 s2, s18, 10
	s_or_b32 s15, s1, 9
	v_lshl_add_u64 v[62:63], s[2:3], 2, v[2:3]
	s_lshl_b32 s2, s15, 10
	s_or_b32 s13, s1, 10
	v_lshl_add_u64 v[66:67], s[2:3], 2, v[2:3]
	s_lshl_b32 s2, s13, 10
	s_or_b32 s12, s1, 11
	global_load_dword v58, v[58:59], off
	s_or_b32 s11, s1, 12
	global_load_dword v60, v[60:61], off
	s_or_b32 s10, s1, 13
	global_load_dword v62, v[62:63], off
	s_or_b32 s7, s1, 14
	global_load_dword v64, v[66:67], off
	v_lshl_add_u64 v[66:67], s[2:3], 2, v[2:3]
	s_lshl_b32 s2, s12, 10
	v_lshl_add_u64 v[78:79], s[2:3], 2, v[2:3]
	s_lshl_b32 s2, s11, 10
	global_load_dword v66, v[66:67], off
	s_or_b32 s6, s1, 15
	global_load_dword v68, v[78:79], off
	v_lshl_add_u64 v[78:79], s[2:3], 2, v[2:3]
	s_lshl_b32 s2, s10, 10
	global_load_dword v70, v[78:79], off
	v_lshl_add_u64 v[78:79], s[2:3], 2, v[2:3]
	s_lshl_b32 s2, s7, 10
	v_mul_lo_u32 v59, s1, v77
	global_load_dword v72, v[78:79], off
	v_lshl_add_u64 v[78:79], s[2:3], 2, v[2:3]
	s_lshl_b32 s2, s6, 10
	v_and_b32_e32 v61, 48, v59
	v_add_u32_e32 v59, s1, v59
	global_load_dword v74, v[78:79], off
	v_lshl_add_u64 v[78:79], s[2:3], 2, v[2:3]
	v_and_b32_e32 v63, 32, v59
	global_load_dword v76, v[78:79], off
	v_lshl_add_u32 v61, v61, 2, 0
	v_lshl_add_u32 v63, v63, 2, 0
	v_add_u32_e32 v59, s1, v59
	ds_read_b32 v61, v61
	ds_read_b32 v94, v63
	v_and_b32_e32 v63, 48, v59
	v_lshl_add_u32 v63, v63, 2, 0
	v_lshl_add_u32 v59, s1, 1, v59
	ds_read_b32 v95, v63
	v_and_b32_e32 v63, 48, v59
	v_lshl_add_u32 v63, v63, 2, 0
	v_add_u32_e32 v59, s1, v59
	ds_read_b32 v99, v63
	v_and_b32_e32 v63, 32, v59
	v_add_u32_e32 v59, s1, v59
	v_and_b32_e32 v59, 48, v59
	v_lshl_add_u32 v59, v59, 2, 0
	v_lshl_add_u32 v63, v63, 2, 0
	ds_read_b32 v101, v59
	v_mul_lo_u32 v59, s25, v32
	ds_read_b32 v100, v63
	v_and_b32_e32 v63, 56, v59
	v_lshl_add_u32 v63, v63, 2, 0
	ds_read_b32 v102, v63
	v_add_u32_e32 v63, s25, v59
	v_and_b32_e32 v67, 57, v63
	v_lshl_add_u32 v67, v67, 2, 0
	v_add_u32_e32 v63, s25, v63
	ds_read_b32 v103, v67
	v_and_b32_e32 v67, 58, v63
	v_lshl_add_u32 v67, v67, 2, 0
	v_add_u32_e32 v63, s25, v63
	ds_read_b32 v104, v67
	v_and_b32_e32 v67, 59, v63
	v_lshl_add_u32 v67, v67, 2, 0
	v_lshl_add_u32 v63, s25, 1, v63
	ds_read2_b32 v[78:79], v97 offset1:32
	ds_read_b32 v105, v67
	ds_read2_b32 v[84:85], v108 offset1:4
	v_and_b32_e32 v67, 61, v63
	v_lshl_add_u32 v67, v67, 2, 0
	v_add_u32_e32 v63, s25, v63
	ds_read_b32 v107, v67
	v_and_b32_e32 v67, 62, v63
	v_add_u32_e32 v63, s25, v63
	v_and_b32_e32 v63, 63, v63
	v_lshl_add_u32 v67, v67, 2, 0
	v_lshl_add_u32 v63, v63, 2, 0
	v_add_u32_e32 v59, v59, v32
	ds_read_b32 v118, v67
	ds_read_b32 v119, v63
	v_and_b32_e32 v63, 48, v59
	v_lshl_add_u32 v63, v63, 2, 0
	ds_read_b32 v120, v63
	v_add_u32_e32 v63, s24, v59
	v_and_b32_e32 v67, 50, v63
	v_lshl_add_u32 v67, v67, 2, 0
	v_add_u32_e32 v63, s24, v63
	ds_read_b32 v121, v67
	v_and_b32_e32 v67, 52, v63
	v_lshl_add_u32 v67, v67, 2, 0
	v_add_u32_e32 v63, s24, v63
	ds_read_b32 v122, v67
	v_and_b32_e32 v67, 54, v63
	v_lshl_add_u32 v67, v67, 2, 0
	v_lshl_add_u32 v63, s24, 1, v63
	ds_read_b32 v123, v67
	ds_read2_b32 v[90:91], v109 offset1:8
	v_and_b32_e32 v67, 58, v63
	v_lshl_add_u32 v67, v67, 2, 0
	v_add_u32_e32 v63, s24, v63
	ds_read_b32 v125, v67
	v_and_b32_e32 v67, 60, v63
	v_add_u32_e32 v63, s24, v63
	v_and_b32_e32 v63, 62, v63
	v_lshl_add_u32 v67, v67, 2, 0
	v_lshl_add_u32 v63, v63, 2, 0
	v_add_u32_e32 v59, v59, v32
	ds_read_b32 v126, v67
	ds_read_b32 v127, v63
	v_and_b32_e32 v63, 56, v59
	v_lshl_add_u32 v63, v63, 2, 0
	ds_read_b32 v128, v63
	v_add_u32_e32 v63, s23, v59
	v_and_b32_e32 v67, 59, v63
	v_lshl_add_u32 v67, v67, 2, 0
	v_add_u32_e32 v63, s23, v63
	ds_read_b32 v129, v67
	v_and_b32_e32 v67, 62, v63
	v_lshl_add_u32 v67, v67, 2, 0
	v_add_u32_e32 v63, s23, v63
	ds_read_b32 v130, v67
	v_and_b32_e32 v67, 57, v63
	v_lshl_add_u32 v67, v67, 2, 0
	v_add_u32_e32 v63, s23, v63
	ds_read_b32 v131, v67
	v_and_b32_e32 v67, 60, v63
	v_lshl_add_u32 v67, v67, 2, 0
	v_add_u32_e32 v63, s23, v63
	ds_read_b32 v132, v67
	v_and_b32_e32 v67, 63, v63
	v_lshl_add_u32 v67, v67, 2, 0
	v_add_u32_e32 v63, s23, v63
	ds_read_b32 v133, v67
	v_and_b32_e32 v67, 58, v63
	v_add_u32_e32 v63, s23, v63
	v_and_b32_e32 v63, 61, v63
	v_lshl_add_u32 v67, v67, 2, 0
	v_lshl_add_u32 v63, v63, 2, 0
	v_add_u32_e32 v59, v59, v32
	ds_read_b32 v134, v67
	ds_read_b32 v135, v63
	v_and_b32_e32 v63, 32, v59
	v_lshl_add_u32 v63, v63, 2, 0
	ds_read_b32 v136, v63
	v_add_u32_e32 v63, s22, v59
	v_and_b32_e32 v67, 52, v63
	v_lshl_add_u32 v67, v67, 2, 0
	v_add_u32_e32 v63, s22, v63
	ds_read_b32 v137, v67
	v_and_b32_e32 v67, 40, v63
	s_waitcnt vmcnt(15) lgkmcnt(14)
	v_pk_fma_f32 v[50:51], v[80:81], v[94:95], v[50:51] op_sel_hi:[0,1,1]
	v_lshl_add_u32 v67, v67, 2, 0
	v_add_u32_e32 v63, s22, v63
	s_waitcnt vmcnt(14)
; #define GAS __attribute__((address_space(1)))
; __device__ void phase_prep(const Params& p, LAS unsigned char* lds) {
;     ...
;             for (int m0 = 0; m0 < 64; m0 += 16) {
;                 float wv[16];
; #pragma unroll
;                 for (int dd = 0; dd < 16; ++dd) wv[dd] = ((GAS const float*)(unsigned long long)wb)[(size_t)(m0 + dd) * 1024];
;                 asm volatile("" ::: "memory");
; #pragma unroll
;                 for (int dd = 0; dd < 16; ++dd) { const int m = m0 + dd; const float w = wv[dd];
; #pragma unroll
;                     for (int q = 0; q < 8; ++q) a[q] += scr[(m * (8 * co + q)) & 63] * w; }
;             }
	v_pk_fma_f32 v[50:51], v[82:83], v[104:105], v[50:51] op_sel_hi:[0,1,1]
	v_mov_b32_e32 v98, v78
	v_mul_f32_e32 v61, v80, v61
	ds_read_b32 v138, v67
	v_and_b32_e32 v67, 60, v63
	s_waitcnt vmcnt(13)
	v_pk_fma_f32 v[50:51], v[86:87], v[122:123], v[50:51] op_sel_hi:[0,1,1]
	v_lshl_add_u32 v63, s22, 1, v63
	v_pk_mul_f32 v[122:123], v[80:81], v[98:99] op_sel_hi:[0,1]
	v_lshl_add_u32 v67, v67, 2, 0
	v_mov_b32_e32 v123, v61
	v_add_u32_e32 v61, s22, v63
	ds_read_b32 v139, v67
	v_and_b32_e32 v67, 52, v63
	v_and_b32_e32 v63, 56, v61
	v_add_u32_e32 v61, s22, v61
	v_and_b32_e32 v61, 60, v61
	ds_read2_b32 v[94:95], v110 offset1:16
	v_lshl_add_u32 v67, v67, 2, 0
	v_lshl_add_u32 v63, v63, 2, 0
	v_lshl_add_u32 v61, v61, 2, 0
	ds_read_b32 v105, v67
	v_pk_fma_f32 v[54:55], v[80:81], v[98:99], v[54:55] op_sel_hi:[0,1,1]
	ds_read_b32 v98, v63
	ds_read_b32 v99, v61
	v_mov_b32_e32 v106, v85
	v_pk_add_f32 v[4:5], v[4:5], v[122:123]
	v_pk_fma_f32 v[52:53], v[80:81], v[100:101], v[52:53] op_sel_hi:[0,1,1]
	v_pk_fma_f32 v[54:55], v[82:83], v[106:107], v[54:55] op_sel_hi:[0,1,1]
	s_waitcnt lgkmcnt(14)
	v_mov_b32_e32 v124, v91
	v_pk_fma_f32 v[4:5], v[82:83], v[102:103], v[4:5] op_sel_hi:[0,1,1]
	v_pk_fma_f32 v[52:53], v[82:83], v[118:119], v[52:53] op_sel_hi:[0,1,1]
	v_add_u32_e32 v59, v59, v32
	v_pk_fma_f32 v[54:55], v[86:87], v[124:125], v[54:55] op_sel_hi:[0,1,1]
	v_pk_fma_f32 v[4:5], v[86:87], v[120:121], v[4:5] op_sel_hi:[0,1,1]
	v_pk_fma_f32 v[52:53], v[86:87], v[126:127], v[52:53] op_sel_hi:[0,1,1]
	v_and_b32_e32 v61, 56, v59
	s_waitcnt vmcnt(12) lgkmcnt(12)
	v_pk_fma_f32 v[50:51], v[88:89], v[130:131], v[50:51] op_sel_hi:[0,1,1]
	s_waitcnt lgkmcnt(10)
	v_pk_fma_f32 v[54:55], v[88:89], v[132:133], v[54:55] op_sel_hi:[0,1,1]
	v_pk_fma_f32 v[4:5], v[88:89], v[128:129], v[4:5] op_sel_hi:[0,1,1]
	s_waitcnt lgkmcnt(3)
	v_mov_b32_e32 v104, v95
	v_pk_fma_f32 v[52:53], v[88:89], v[134:135], v[52:53] op_sel_hi:[0,1,1]
	v_lshl_add_u32 v61, v61, 2, 0
	s_waitcnt vmcnt(11)
	v_pk_fma_f32 v[50:51], v[92:93], v[138:139], v[50:51] op_sel_hi:[0,1,1]
	v_pk_fma_f32 v[4:5], v[92:93], v[136:137], v[4:5] op_sel_hi:[0,1,1]
	s_waitcnt lgkmcnt(2)
	v_pk_fma_f32 v[54:55], v[92:93], v[104:105], v[54:55] op_sel_hi:[0,1,1]
	s_waitcnt lgkmcnt(0)
	v_pk_fma_f32 v[52:53], v[92:93], v[98:99], v[52:53] op_sel_hi:[0,1,1]
	ds_read_b32 v92, v61
	v_add_u32_e32 v61, s21, v59
	v_and_b32_e32 v63, 61, v61
	v_lshl_add_u32 v63, v63, 2, 0
	v_add_u32_e32 v61, s21, v61
	ds_read_b32 v93, v63
	v_and_b32_e32 v63, 58, v61
	v_lshl_add_u32 v63, v63, 2, 0
	v_add_u32_e32 v61, s21, v61
	ds_read_b32 v86, v63
	v_and_b32_e32 v63, 63, v61
	v_lshl_add_u32 v63, v63, 2, 0
	v_add_u32_e32 v61, s21, v61
	ds_read_b32 v87, v63
	v_and_b32_e32 v63, 60, v61
	v_lshl_add_u32 v63, v63, 2, 0
	v_add_u32_e32 v61, s21, v61
	ds_read_b32 v82, v63
	v_and_b32_e32 v63, 57, v61
	v_lshl_add_u32 v63, v63, 2, 0
	v_add_u32_e32 v61, s21, v61
	ds_read_b32 v83, v63
	v_and_b32_e32 v63, 62, v61
	v_add_u32_e32 v61, s21, v61
	v_and_b32_e32 v61, 59, v61
	v_lshl_add_u32 v63, v63, 2, 0
	v_lshl_add_u32 v61, v61, 2, 0
	v_add_u32_e32 v59, v59, v32
	ds_read_b32 v80, v63
	ds_read_b32 v81, v61
	v_and_b32_e32 v61, 48, v59
	v_lshl_add_u32 v61, v61, 2, 0
	ds_read_b32 v104, v61
	v_add_u32_e32 v61, s20, v59
	v_and_b32_e32 v63, 54, v61
	v_lshl_add_u32 v63, v63, 2, 0
	v_add_u32_e32 v61, s20, v61
	ds_read_b32 v105, v63
	v_and_b32_e32 v63, 60, v61
	v_lshl_add_u32 v63, v63, 2, 0
	v_add_u32_e32 v61, s20, v61
	ds_read_b32 v100, v63
	v_and_b32_e32 v63, 50, v61
	v_lshl_add_u32 v63, v63, 2, 0
	v_add_u32_e32 v61, s20, v61
	ds_read_b32 v101, v63
	v_and_b32_e32 v63, 56, v61
	v_lshl_add_u32 v63, v63, 2, 0
	v_add_u32_e32 v61, s20, v61
	ds_read_b32 v98, v63
	v_and_b32_e32 v63, 62, v61
	v_lshl_add_u32 v63, v63, 2, 0
	v_add_u32_e32 v61, s20, v61
	ds_read_b32 v99, v63
	v_and_b32_e32 v63, 52, v61
	v_add_u32_e32 v61, s20, v61
	v_and_b32_e32 v61, 58, v61
	v_lshl_add_u32 v63, v63, 2, 0
	v_lshl_add_u32 v61, v61, 2, 0
	v_add_u32_e32 v59, v59, v32
	ds_read_b32 v88, v63
	ds_read_b32 v89, v61
	v_and_b32_e32 v61, 56, v59
	v_lshl_add_u32 v61, v61, 2, 0
	v_add_u32_e32 v59, s19, v59
	ds_read_b32 v118, v61
	v_and_b32_e32 v61, 63, v59
	v_lshl_add_u32 v61, v61, 2, 0
	ds_read_b32 v119, v61
	v_add_u32_e32 v61, s19, v59
	v_and_b32_e32 v63, 62, v61
	v_lshl_add_u32 v63, v63, 2, 0
	v_add_u32_e32 v61, s19, v61
	ds_read_b32 v120, v63
	v_and_b32_e32 v63, 61, v61
	v_lshl_add_u32 v63, v63, 2, 0
	v_add_u32_e32 v61, s19, v61
	ds_read_b32 v121, v63
	v_and_b32_e32 v63, 60, v61
	v_lshl_add_u32 v63, v63, 2, 0
	v_add_u32_e32 v61, s19, v61
	ds_read_b32 v106, v63
	v_and_b32_e32 v63, 59, v61
	v_lshl_add_u32 v63, v63, 2, 0
	v_add_u32_e32 v61, s19, v61
	ds_read_b32 v107, v63
	v_and_b32_e32 v63, 58, v61
	v_add_u32_e32 v61, s19, v61
	v_and_b32_e32 v61, 57, v61
	v_lshl_add_u32 v63, v63, 2, 0
	v_lshl_add_u32 v61, v61, 2, 0
	v_add_u32_e32 v59, v59, v77
	ds_read_b32 v102, v63
	ds_read_b32 v103, v61
	v_and_b32_e32 v61, 56, v59
	v_lshl_add_u32 v61, v61, 2, 0
	ds_read_b32 v123, v61
	v_add_u32_e32 v61, s18, v59
	v_and_b32_e32 v63, 48, v61
	v_lshl_add_u32 v63, v63, 2, 0
	v_add_u32_e32 v61, s18, v61
	ds_read_b32 v124, v63
	v_and_b32_e32 v63, 56, v61
	v_lshl_add_u32 v63, v63, 2, 0
	v_lshl_add_u32 v61, s18, 1, v61
	ds_read_b32 v125, v63
	v_and_b32_e32 v63, 56, v61
	v_lshl_add_u32 v63, v63, 2, 0
	v_add_u32_e32 v61, s18, v61
	ds_read_b32 v127, v63
	v_and_b32_e32 v63, 48, v61
	v_add_u32_e32 v61, s18, v61
	v_and_b32_e32 v61, 56, v61
	v_lshl_add_u32 v63, v63, 2, 0
	v_lshl_add_u32 v61, v61, 2, 0
	v_add_u32_e32 v59, v59, v77
	ds_read_b32 v128, v63
	ds_read_b32 v129, v61
	v_and_b32_e32 v61, 57, v59
	v_lshl_add_u32 v61, v61, 2, 0
	ds_read_b32 v85, v61
; __device__ void phase_prep(const Params& p, LAS unsigned char* lds) {
;     ...
;                 for (int dd = 0; dd < 16; ++dd) { const int m = m0 + dd; const float w = wv[dd];
; #pragma unroll
;                     for (int q = 0; q < 8; ++q) a[q] += scr[(m * (8 * co + q)) & 63] * w; }
;             }
	v_add_u32_e32 v61, s15, v59
	v_and_b32_e32 v63, 58, v61
	v_lshl_add_u32 v63, v63, 2, 0
	v_add_u32_e32 v61, s15, v61
	ds_read_b32 v130, v63
	v_and_b32_e32 v63, 59, v61
	v_lshl_add_u32 v63, v63, 2, 0
	v_add_u32_e32 v61, s15, v61
	ds_read_b32 v131, v63
	v_and_b32_e32 v63, 60, v61
	v_lshl_add_u32 v63, v63, 2, 0
	v_add_u32_e32 v61, s15, v61
	ds_read_b32 v132, v63
	v_and_b32_e32 v63, 61, v61
	v_lshl_add_u32 v63, v63, 2, 0
	v_add_u32_e32 v61, s15, v61
	ds_read_b32 v133, v63
	v_and_b32_e32 v63, 62, v61
	v_add_u32_e32 v61, s15, v61
	v_and_b32_e32 v61, 63, v61
	v_lshl_add_u32 v63, v63, 2, 0
	v_lshl_add_u32 v61, v61, 2, 0
	v_add_u32_e32 v59, v59, v77
	ds_read_b32 v134, v63
	ds_read_b32 v135, v61
	v_and_b32_e32 v61, 58, v59
	v_lshl_add_u32 v61, v61, 2, 0
	ds_read_b32 v91, v61
	v_add_u32_e32 v61, s13, v59
	v_and_b32_e32 v63, 52, v61
	v_lshl_add_u32 v63, v63, 2, 0
	v_add_u32_e32 v61, s13, v61
	ds_read_b32 v136, v63
	v_and_b32_e32 v63, 62, v61
	v_lshl_add_u32 v63, v63, 2, 0
	v_add_u32_e32 v61, s13, v61
	ds_read_b32 v137, v63
	v_and_b32_e32 v63, 56, v61
	v_lshl_add_u32 v63, v63, 2, 0
	v_add_u32_e32 v61, s13, v61
	ds_read_b32 v138, v63
	v_and_b32_e32 v63, 50, v61
	v_lshl_add_u32 v63, v63, 2, 0
	v_add_u32_e32 v61, s13, v61
	ds_read_b32 v139, v63
	v_and_b32_e32 v63, 60, v61
	v_add_u32_e32 v61, s13, v61
	v_and_b32_e32 v61, 54, v61
	v_lshl_add_u32 v63, v63, 2, 0
	v_lshl_add_u32 v61, v61, 2, 0
	v_add_u32_e32 v59, v59, v77
	ds_read_b32 v140, v63
	ds_read_b32 v141, v61
	ds_read_b32 v142, v111
	v_and_b32_e32 v61, 59, v59
	v_lshl_add_u32 v61, v61, 2, 0
	ds_read_b32 v143, v61
	v_add_u32_e32 v61, s12, v59
	v_and_b32_e32 v63, 62, v61
	v_lshl_add_u32 v63, v63, 2, 0
	v_add_u32_e32 v61, s12, v61
	ds_read_b32 v144, v63
	v_and_b32_e32 v63, 57, v61
	v_lshl_add_u32 v63, v63, 2, 0
	v_add_u32_e32 v61, s12, v61
	ds_read_b32 v145, v63
	v_and_b32_e32 v63, 60, v61
	v_lshl_add_u32 v63, v63, 2, 0
	v_add_u32_e32 v61, s12, v61
	ds_read_b32 v146, v63
	v_and_b32_e32 v63, 63, v61
	v_lshl_add_u32 v63, v63, 2, 0
	v_add_u32_e32 v61, s12, v61
	ds_read_b32 v147, v63
	v_and_b32_e32 v63, 58, v61
	v_add_u32_e32 v61, s12, v61
	v_and_b32_e32 v61, 61, v61
	v_lshl_add_u32 v63, v63, 2, 0
	v_lshl_add_u32 v61, v61, 2, 0
	v_add_u32_e32 v59, v59, v77
	ds_read_b32 v148, v63
	ds_read_b32 v149, v61
	v_and_b32_e32 v61, 60, v59
	v_lshl_add_u32 v61, v61, 2, 0
	ds_read_b32 v95, v61
	v_add_u32_e32 v61, s11, v59
	v_and_b32_e32 v63, 56, v61
	v_lshl_add_u32 v63, v63, 2, 0
	v_add_u32_e32 v61, s11, v61
	ds_read_b32 v150, v63
	v_and_b32_e32 v63, 52, v61
	v_lshl_add_u32 v63, v63, 2, 0
	v_add_u32_e32 v61, s11, v61
	ds_read_b32 v151, v63
	v_and_b32_e32 v63, 48, v61
	v_lshl_add_u32 v63, v63, 2, 0
	v_add_u32_e32 v61, s11, v61
	ds_read_b32 v152, v63
	v_and_b32_e32 v63, 60, v61
	v_lshl_add_u32 v63, v63, 2, 0
	v_add_u32_e32 v61, s11, v61
	ds_read_b32 v153, v63
	v_and_b32_e32 v63, 40, v61
	v_add_u32_e32 v61, s11, v61
	v_and_b32_e32 v61, 52, v61
	v_lshl_add_u32 v63, v63, 2, 0
	v_lshl_add_u32 v61, v61, 2, 0
	v_add_u32_e32 v59, v59, v77
	ds_read_b32 v154, v63
	ds_read_b32 v155, v61
	ds_read_b32 v156, v112
	v_and_b32_e32 v61, 61, v59
	v_lshl_add_u32 v61, v61, 2, 0
	ds_read_b32 v157, v61
	v_add_u32_e32 v61, s10, v59
	v_and_b32_e32 v63, 58, v61
	v_lshl_add_u32 v63, v63, 2, 0
	v_add_u32_e32 v61, s10, v61
	ds_read_b32 v158, v63
	v_and_b32_e32 v63, 63, v61
	v_lshl_add_u32 v63, v63, 2, 0
	v_add_u32_e32 v61, s10, v61
	ds_read_b32 v159, v63
	v_and_b32_e32 v63, 60, v61
	v_lshl_add_u32 v63, v63, 2, 0
	v_add_u32_e32 v61, s10, v61
	ds_read_b32 v160, v63
	v_and_b32_e32 v63, 57, v61
	v_lshl_add_u32 v63, v63, 2, 0
	v_add_u32_e32 v61, s10, v61
	ds_read_b32 v161, v63
	v_and_b32_e32 v63, 62, v61
	v_add_u32_e32 v61, s10, v61
	v_and_b32_e32 v61, 59, v61
	v_lshl_add_u32 v63, v63, 2, 0
	v_lshl_add_u32 v61, v61, 2, 0
	v_add_u32_e32 v59, v59, v77
	ds_read_b32 v162, v63
	ds_read_b32 v163, v61
	ds_read_b32 v164, v113
	v_and_b32_e32 v61, 62, v59
	v_lshl_add_u32 v61, v61, 2, 0
	ds_read_b32 v165, v61
	v_add_u32_e32 v61, s7, v59
	v_and_b32_e32 v63, 60, v61
	v_lshl_add_u32 v63, v63, 2, 0
	v_add_u32_e32 v61, s7, v61
	ds_read_b32 v166, v63
	v_and_b32_e32 v63, 58, v61
	v_lshl_add_u32 v63, v63, 2, 0
	v_add_u32_e32 v61, s7, v61
	ds_read_b32 v167, v63
	v_and_b32_e32 v63, 56, v61
	v_lshl_add_u32 v63, v63, 2, 0
	v_add_u32_e32 v61, s7, v61
	ds_read_b32 v168, v63
	v_and_b32_e32 v63, 54, v61
	v_lshl_add_u32 v63, v63, 2, 0
	v_add_u32_e32 v61, s7, v61
	ds_read_b32 v169, v63
	v_and_b32_e32 v63, 52, v61
	v_add_u32_e32 v61, s7, v61
	v_and_b32_e32 v61, 50, v61
	v_lshl_add_u32 v63, v63, 2, 0
	v_lshl_add_u32 v61, v61, 2, 0
	v_add_u32_e32 v59, v59, v77
	ds_read_b32 v170, v63
	ds_read_b32 v171, v61
	ds_read_b32 v172, v75
	v_and_b32_e32 v61, 63, v59
	s_waitcnt vmcnt(10) lgkmcnt(14)
	v_pk_fma_f32 v[4:5], v[56:57], v[92:93], v[4:5] op_sel_hi:[0,1,1]
	v_lshl_add_u32 v61, v61, 2, 0
	s_waitcnt vmcnt(9)
; __device__ __forceinline__ unsigned pk2(float lo, float hi) { unsigned r; asm volatile("v_cvt_pk_bf16_f32 %0, %1, %2" : "=v"(r) : "v"(lo), "v"(hi)); return r; }
; __device__ void phase_prep(const Params& p, LAS unsigned char* lds) {
;     ...
;                 for (int dd = 0; dd < 16; ++dd) { const int m = m0 + dd; const float w = wv[dd];
; #pragma unroll
;                     for (int q = 0; q < 8; ++q) a[q] += scr[(m * (8 * co + q)) & 63] * w; }
;             }
;             bf16_t* dst = (bf16_t*)(p.ws + OFF_W + (size_t)l * LW + LW_WM) + (size_t)n * 1280 + 768 + g * 128 + part * 64 + 8 * co;
;             u32x4 o; o.x = pk2(a[0], a[1]); o.y = pk2(a[2], a[3]); o.z = pk2(a[4], a[5]); o.w = pk2(a[6], a[7]);
;             *(u32x4*)dst = o;
	v_pk_fma_f32 v[4:5], v[58:59], v[104:105], v[4:5] op_sel_hi:[0,1,1]
	v_add_u32_e32 v59, s6, v59
	ds_read_b32 v173, v61
	s_waitcnt vmcnt(8)
	v_pk_fma_f32 v[4:5], v[60:61], v[118:119], v[4:5] op_sel_hi:[0,1,1]
	v_mov_b32_e32 v122, v78
	v_and_b32_e32 v61, 62, v59
	s_waitcnt vmcnt(7)
	v_pk_fma_f32 v[4:5], v[62:63], v[122:123], v[4:5] op_sel_hi:[0,1,1]
	v_lshl_add_u32 v61, v61, 2, 0
	v_add_u32_e32 v59, s6, v59
	s_waitcnt vmcnt(6)
	v_pk_fma_f32 v[4:5], v[64:65], v[84:85], v[4:5] op_sel_hi:[0,1,1]
	ds_read_b32 v84, v61
	v_and_b32_e32 v61, 61, v59
	v_pk_fma_f32 v[50:51], v[56:57], v[86:87], v[50:51] op_sel_hi:[0,1,1]
	v_lshl_add_u32 v61, v61, 2, 0
	v_pk_fma_f32 v[50:51], v[58:59], v[100:101], v[50:51] op_sel_hi:[0,1,1]
	v_pk_fma_f32 v[50:51], v[60:61], v[120:121], v[50:51] op_sel_hi:[0,1,1]
	v_pk_fma_f32 v[50:51], v[62:63], v[124:125], v[50:51] op_sel_hi:[0,1,1]
	v_pk_fma_f32 v[50:51], v[64:65], v[130:131], v[50:51] op_sel_hi:[0,1,1]
	ds_read_b32 v85, v61
	s_waitcnt vmcnt(5)
	v_pk_fma_f32 v[50:51], v[66:67], v[136:137], v[50:51] op_sel_hi:[0,1,1]
	s_waitcnt vmcnt(4)
	v_pk_fma_f32 v[50:51], v[68:69], v[144:145], v[50:51] op_sel_hi:[0,1,1]
	s_waitcnt vmcnt(3)
	v_pk_fma_f32 v[50:51], v[70:71], v[150:151], v[50:51] op_sel_hi:[0,1,1]
	v_add_u32_e32 v59, s6, v59
	s_waitcnt vmcnt(2) lgkmcnt(14)
	v_pk_fma_f32 v[50:51], v[72:73], v[158:159], v[50:51] op_sel_hi:[0,1,1]
	v_and_b32_e32 v61, 60, v59
	s_waitcnt vmcnt(1) lgkmcnt(8)
	v_pk_fma_f32 v[50:51], v[74:75], v[166:167], v[50:51] op_sel_hi:[0,1,1]
	v_lshl_add_u32 v61, v61, 2, 0
	v_add_u32_e32 v59, s6, v59
	s_waitcnt vmcnt(0) lgkmcnt(0)
	v_pk_fma_f32 v[50:51], v[76:77], v[84:85], v[50:51] op_sel_hi:[0,1,1]
	ds_read_b32 v84, v61
	v_and_b32_e32 v61, 59, v59
	v_pk_fma_f32 v[54:55], v[56:57], v[82:83], v[54:55] op_sel_hi:[0,1,1]
	v_lshl_add_u32 v61, v61, 2, 0
	v_pk_fma_f32 v[54:55], v[58:59], v[98:99], v[54:55] op_sel_hi:[0,1,1]
	v_add_u32_e32 v59, s6, v59
	ds_read_b32 v85, v61
	v_pk_fma_f32 v[54:55], v[60:61], v[106:107], v[54:55] op_sel_hi:[0,1,1]
	v_and_b32_e32 v61, 58, v59
	v_add_u32_e32 v59, s6, v59
	v_and_b32_e32 v59, 57, v59
	v_lshl_add_u32 v59, v59, 2, 0
	v_pk_fma_f32 v[52:53], v[56:57], v[80:81], v[52:53] op_sel_hi:[0,1,1]
	v_lshl_add_u32 v61, v61, 2, 0
	v_pk_fma_f32 v[52:53], v[58:59], v[88:89], v[52:53] op_sel_hi:[0,1,1]
	v_mov_b32_e32 v126, v79
	v_pk_fma_f32 v[52:53], v[60:61], v[102:103], v[52:53] op_sel_hi:[0,1,1]
	v_pk_fma_f32 v[54:55], v[62:63], v[126:127], v[54:55] op_sel_hi:[0,1,1]
	v_pk_fma_f32 v[52:53], v[62:63], v[128:129], v[52:53] op_sel_hi:[0,1,1]
	v_pk_fma_f32 v[54:55], v[64:65], v[132:133], v[54:55] op_sel_hi:[0,1,1]
	v_pk_fma_f32 v[52:53], v[64:65], v[134:135], v[52:53] op_sel_hi:[0,1,1]
	v_pk_fma_f32 v[4:5], v[66:67], v[90:91], v[4:5] op_sel_hi:[0,1,1]
	v_pk_fma_f32 v[54:55], v[66:67], v[138:139], v[54:55] op_sel_hi:[0,1,1]
	ds_read_b32 v78, v61
	ds_read_b32 v79, v59
	v_pk_fma_f32 v[52:53], v[66:67], v[140:141], v[52:53] op_sel_hi:[0,1,1]
	v_pk_fma_f32 v[4:5], v[68:69], v[142:143], v[4:5] op_sel_hi:[0,1,1]
	v_pk_fma_f32 v[54:55], v[68:69], v[146:147], v[54:55] op_sel_hi:[0,1,1]
	v_pk_fma_f32 v[52:53], v[68:69], v[148:149], v[52:53] op_sel_hi:[0,1,1]
	v_pk_fma_f32 v[4:5], v[70:71], v[94:95], v[4:5] op_sel_hi:[0,1,1]
	v_pk_fma_f32 v[54:55], v[70:71], v[152:153], v[54:55] op_sel_hi:[0,1,1]
	v_pk_fma_f32 v[52:53], v[70:71], v[154:155], v[52:53] op_sel_hi:[0,1,1]
	v_pk_fma_f32 v[4:5], v[72:73], v[156:157], v[4:5] op_sel_hi:[0,1,1]
	v_pk_fma_f32 v[54:55], v[72:73], v[160:161], v[54:55] op_sel_hi:[0,1,1]
	v_pk_fma_f32 v[52:53], v[72:73], v[162:163], v[52:53] op_sel_hi:[0,1,1]
	v_pk_fma_f32 v[4:5], v[74:75], v[164:165], v[4:5] op_sel_hi:[0,1,1]
	v_pk_fma_f32 v[54:55], v[74:75], v[168:169], v[54:55] op_sel_hi:[0,1,1]
	v_pk_fma_f32 v[52:53], v[74:75], v[170:171], v[52:53] op_sel_hi:[0,1,1]
	s_add_i32 s2, s1, 16
	v_pk_fma_f32 v[4:5], v[76:77], v[172:173], v[4:5] op_sel_hi:[0,1,1]
	s_waitcnt lgkmcnt(2)
	v_pk_fma_f32 v[54:55], v[76:77], v[84:85], v[54:55] op_sel_hi:[0,1,1]
	s_waitcnt lgkmcnt(0)
	v_pk_fma_f32 v[52:53], v[76:77], v[78:79], v[52:53] op_sel_hi:[0,1,1]
	s_cmp_gt_u32 s1, 47
	s_mov_b32 s1, s2
	s_cbranch_scc0 .LBB0_693
	s_mul_hi_u32 s1, s0, 0x1d80000
	s_mul_i32 s0, s0, 0x1d80000
	v_lshl_add_u64 v[2:3], v[24:25], 0, s[0:1]
	v_mad_u64_u32 v[2:3], s[0:1], v57, s38, v[2:3]
	s_lshl_b32 s2, s5, 5
	v_lshl_add_u64 v[2:3], v[2:3], 0, s[2:3]
	s_lshl_b32 s2, s4, 3
	v_lshl_add_u64 v[2:3], v[2:3], 0, s[2:3]
	v_and_b32_e32 v56, 24, v32
	v_lshlrev_b32_e32 v56, 5, v56
	v_lshrrev_b32_e32 v57, 5, v32
	v_lshl_or_b32 v56, v57, 4, v56
	v_mov_b32_e32 v57, 0
	v_lshl_add_u64 v[56:57], v[56:57], 0, v[2:3]
	v_cvt_pk_bf16_f32 v2, v4, v5
	v_cvt_pk_bf16_f32 v3, v50, v51
	v_add_co_u32_e32 v50, vcc, 0xe80000, v56
	v_cvt_pk_bf16_f32 v4, v54, v55
	v_cvt_pk_bf16_f32 v5, v52, v53
	s_nop 1
	v_addc_co_u32_e32 v51, vcc, 0, v57, vcc
	global_store_dwordx2 v[50:51], v[2:3], off offset:1536
	global_store_dwordx2 v[50:51], v[4:5], off offset:1664
	s_waitcnt lgkmcnt(0)
	s_barrier
